# grid barrier: XCD leader issues its L1 invalidate right after its release write-back; per-XCD generation bump dropped
# speedup vs baseline: 1.0135x; 1.0023x over previous
.LBB0_111:
	s_andn2_saveexec_b64 s[2:3], s[6:7]
	s_cbranch_execz .LBB0_131
	s_mov_b64 s[6:7], exec
	buffer_wbl2 sc1
	s_waitcnt lgkmcnt(0)
	s_waitcnt vmcnt(0)
	buffer_inv sc1
	v_mbcnt_lo_u32_b32 v2, s6, 0
	v_mbcnt_hi_u32_b32 v2, s7, v2
	v_cmp_eq_u32_e32 vcc, 0, v2
	s_and_saveexec_b64 s[8:9], vcc
	s_cbranch_execz .LBB0_114
	s_bcnt1_i32_b64 s2, s[6:7]
	v_mov_b32_e32 v3, 0x3000
	v_mov_b32_e32 v4, s2
	global_atomic_add v3, v3, v4, s[64:65] offset:1024 sc0

.LBB0_128:
	s_or_b64 exec, exec, s[6:7]
	s_mov_b64 s[6:7], exec
	v_mbcnt_lo_u32_b32 v1, s6, 0
	v_mbcnt_hi_u32_b32 v1, s7, v1
	v_cmp_eq_u32_e32 vcc, 0, v1
	s_waitcnt vmcnt(0)
	s_and_saveexec_b64 s[8:9], vcc
	s_cbranch_execz .LBB0_130
	s_bcnt1_i32_b64 s2, s[6:7]
	v_mov_b32_e32 v1, 0x2000
	v_mov_b32_e32 v2, s2

.LBB0_447:
	s_andn2_saveexec_b64 s[2:3], s[6:7]
	s_cbranch_execz .LBB0_467
	s_mov_b64 s[6:7], exec
	buffer_wbl2 sc1
	s_waitcnt lgkmcnt(0)
	s_waitcnt vmcnt(0)
	buffer_inv sc1
	v_mbcnt_lo_u32_b32 v2, s6, 0
	v_mbcnt_hi_u32_b32 v2, s7, v2
	v_cmp_eq_u32_e32 vcc, 0, v2
	s_and_saveexec_b64 s[8:9], vcc
	s_cbranch_execz .LBB0_450
	s_bcnt1_i32_b64 s2, s[6:7]
	v_mov_b32_e32 v3, 0x3000
	v_mov_b32_e32 v4, s2
	global_atomic_add v3, v3, v4, s[80:81] offset:1024 sc0

.LBB0_1972:
	s_or_b64 exec, exec, s[2:3]
	s_mov_b64 s[2:3], exec
	v_mbcnt_lo_u32_b32 v1, s2, 0
	v_mbcnt_hi_u32_b32 v1, s3, v1
	v_cmp_eq_u32_e32 vcc, 0, v1
	s_waitcnt vmcnt(0)
	s_and_saveexec_b64 s[6:7], vcc
	s_cbranch_execz .LBB0_1974
	s_bcnt1_i32_b64 s2, s[2:3]
	v_mov_b32_e32 v1, 0x2000
	v_mov_b32_e32 v2, s2
